# V-fragment read hoisting (before the exps, into free VGPRs) applied to the sliding-window loop as well
# baseline (speedup 1.0000x reference)
.LBB0_784:
	v_add3_u32 v184, s75, v167, v168
	v_lshl_add_u32 v185, v169, 1, v184
	v_lshl_add_u32 v186, v170, 1, v184
	v_lshl_add_u32 v187, v171, 1, v184
	v_lshl_add_u32 v184, v172, 1, v184
	ds_read_b64 v[188:189], v185 offset:8192
	ds_read_b64 v[190:191], v186 offset:8192
	ds_read_b64 v[192:193], v185 offset:10240
	ds_read_b64 v[194:195], v186 offset:10240
	ds_read_b64 v[196:197], v185 offset:12288
	ds_read_b64 v[198:199], v186 offset:12288
	ds_read_b64 v[200:201], v185 offset:14336
	ds_read_b64 v[202:203], v186 offset:14336
	ds_read_b64 v[204:205], v187 offset:8192
	ds_read_b64 v[206:207], v184 offset:8192
	ds_read_b64 v[208:209], v187 offset:10240
	ds_read_b64 v[210:211], v184 offset:10240
	ds_read_b64 v[212:213], v187 offset:12288
	ds_read_b64 v[214:215], v184 offset:12288
	ds_read_b64 v[216:217], v187 offset:14336
	ds_read_b64 v[218:219], v184 offset:14336
	v_exp_f32_e32 v2, v132
	v_exp_f32_e32 v3, v133
	v_exp_f32_e32 v116, v116
	v_exp_f32_e32 v117, v117
	v_exp_f32_e32 v132, v134
	v_exp_f32_e32 v133, v135
	v_exp_f32_e32 v124, v124
	v_exp_f32_e32 v125, v125
	v_exp_f32_e32 v126, v126
	v_exp_f32_e32 v127, v127
	v_exp_f32_e32 v120, v120
	v_exp_f32_e32 v121, v121
	v_exp_f32_e32 v122, v122
	v_exp_f32_e32 v123, v123
	v_exp_f32_e32 v134, v118
	v_exp_f32_e32 v135, v119
	v_exp_f32_e32 v174, v136
	v_exp_f32_e32 v177, v137
	v_exp_f32_e32 v138, v138
	v_exp_f32_e32 v139, v139
	v_exp_f32_e32 v178, v128
	v_exp_f32_e32 v179, v129
	v_exp_f32_e32 v180, v130
	v_exp_f32_e32 v181, v131
	v_exp_f32_e32 v140, v140
	v_exp_f32_e32 v141, v141
	v_exp_f32_e32 v142, v142
	v_exp_f32_e32 v143, v143
	v_exp_f32_e32 v144, v144
	v_exp_f32_e32 v145, v145
	v_exp_f32_e32 v146, v146
	v_exp_f32_e32 v147, v147
	v_cvt_pk_bf16_f32 v118, v2, v3
	v_cvt_pk_bf16_f32 v120, v120, v121
	v_cvt_pk_bf16_f32 v121, v122, v123
	v_cvt_pk_bf16_f32 v122, v124, v125
	v_cvt_pk_bf16_f32 v124, v116, v117
	v_cvt_pk_bf16_f32 v119, v132, v133
	v_cvt_pk_bf16_f32 v123, v126, v127
	v_cvt_pk_bf16_f32 v125, v134, v135
	s_andn2_b64 vcc, exec, s[30:31]
	s_waitcnt lgkmcnt(0)
	s_nop 0
	v_mfma_f32_16x16x32_bf16 v[72:75], v[188:191], v[118:121], v[72:75]
	v_mfma_f32_16x16x32_bf16 v[36:39], v[188:191], v[122:125], v[36:39]
	v_mfma_f32_16x16x32_bf16 v[68:71], v[192:195], v[118:121], v[68:71]
	v_mfma_f32_16x16x32_bf16 v[32:35], v[192:195], v[122:125], v[32:35]
	v_mfma_f32_16x16x32_bf16 v[64:67], v[196:199], v[118:121], v[64:67]
	v_mfma_f32_16x16x32_bf16 v[28:31], v[196:199], v[122:125], v[28:31]
	v_mfma_f32_16x16x32_bf16 v[56:59], v[200:203], v[118:121], v[56:59]
	v_mfma_f32_16x16x32_bf16 v[24:27], v[200:203], v[122:125], v[24:27]
	v_mfma_f32_16x16x32_bf16 v[112:115], v[20:23], v[118:121], v[112:115]
	v_cvt_pk_bf16_f32 v118, v174, v177
	v_cvt_pk_bf16_f32 v119, v138, v139
	v_cvt_pk_bf16_f32 v120, v140, v141
	v_mfma_f32_16x16x32_bf16 v[76:79], v[20:23], v[122:125], v[76:79]
	v_cvt_pk_bf16_f32 v121, v142, v143
	v_cvt_pk_bf16_f32 v122, v178, v179
	v_cvt_pk_bf16_f32 v123, v180, v181
	v_cvt_pk_bf16_f32 v124, v144, v145
	v_cvt_pk_bf16_f32 v125, v146, v147
	s_nop 1
	v_mfma_f32_16x16x32_bf16 v[72:75], v[204:207], v[118:121], v[72:75]
	v_mfma_f32_16x16x32_bf16 v[36:39], v[204:207], v[122:125], v[36:39]
	v_mfma_f32_16x16x32_bf16 v[68:71], v[208:211], v[118:121], v[68:71]
	v_mfma_f32_16x16x32_bf16 v[32:35], v[208:211], v[122:125], v[32:35]
	v_mfma_f32_16x16x32_bf16 v[112:115], v[20:23], v[118:121], v[112:115]
	v_mfma_f32_16x16x32_bf16 v[76:79], v[20:23], v[122:125], v[76:79]
	v_mfma_f32_16x16x32_bf16 v[64:67], v[212:215], v[118:121], v[64:67]
	v_mfma_f32_16x16x32_bf16 v[28:31], v[212:215], v[122:125], v[28:31]
	v_mfma_f32_16x16x32_bf16 v[56:59], v[216:219], v[118:121], v[56:59]
	v_mfma_f32_16x16x32_bf16 v[24:27], v[216:219], v[122:125], v[24:27]
	s_cbranch_vccnz .LBB0_786
	ds_read_b64 v[220:221], v185 offset:24576
	ds_read_b64 v[222:223], v186 offset:24576
	ds_read_b64 v[224:225], v185 offset:26624
	ds_read_b64 v[226:227], v186 offset:26624
	ds_read_b64 v[228:229], v185 offset:28672
	ds_read_b64 v[230:231], v186 offset:28672
	ds_read_b64 v[232:233], v185 offset:30720
	ds_read_b64 v[234:235], v186 offset:30720
	ds_read_b64 v[188:189], v187 offset:24576
	ds_read_b64 v[190:191], v184 offset:24576
	ds_read_b64 v[192:193], v187 offset:26624
	ds_read_b64 v[194:195], v184 offset:26624
	ds_read_b64 v[196:197], v187 offset:28672
	ds_read_b64 v[198:199], v184 offset:28672
	ds_read_b64 v[200:201], v187 offset:30720
	ds_read_b64 v[202:203], v184 offset:30720
	v_exp_f32_e32 v96, v96
	v_exp_f32_e32 v97, v97
	v_exp_f32_e32 v98, v98
	v_exp_f32_e32 v99, v99
	v_exp_f32_e32 v88, v88
	v_exp_f32_e32 v89, v89
	v_exp_f32_e32 v90, v90
	v_exp_f32_e32 v91, v91
	v_exp_f32_e32 v84, v84
	v_exp_f32_e32 v85, v85
	v_exp_f32_e32 v86, v86
	v_exp_f32_e32 v87, v87
	v_exp_f32_e32 v80, v80
	v_exp_f32_e32 v81, v81
	v_exp_f32_e32 v82, v82
	v_exp_f32_e32 v83, v83
	v_cvt_pk_bf16_f32 v118, v96, v97
	v_cvt_pk_bf16_f32 v119, v98, v99
	v_cvt_pk_bf16_f32 v120, v84, v85
	v_cvt_pk_bf16_f32 v121, v86, v87
	v_cvt_pk_bf16_f32 v122, v88, v89
	v_cvt_pk_bf16_f32 v123, v90, v91
	v_cvt_pk_bf16_f32 v124, v80, v81
	v_cvt_pk_bf16_f32 v125, v82, v83
	s_waitcnt lgkmcnt(0)
	s_nop 0
	v_mfma_f32_16x16x32_bf16 v[72:75], v[220:223], v[118:121], v[72:75]
	v_mfma_f32_16x16x32_bf16 v[36:39], v[220:223], v[122:125], v[36:39]
	v_exp_f32_e32 v100, v100
	v_exp_f32_e32 v101, v101
	v_mfma_f32_16x16x32_bf16 v[76:79], v[20:23], v[122:125], v[76:79]
	v_exp_f32_e32 v102, v102
	v_exp_f32_e32 v103, v103
	v_exp_f32_e32 v92, v92
	v_mfma_f32_16x16x32_bf16 v[68:71], v[224:227], v[118:121], v[68:71]
	v_exp_f32_e32 v93, v93
	v_exp_f32_e32 v94, v94
	v_exp_f32_e32 v95, v95
	v_mfma_f32_16x16x32_bf16 v[32:35], v[224:227], v[122:125], v[32:35]
	v_exp_f32_e32 v104, v104
	v_exp_f32_e32 v105, v105
	v_mfma_f32_16x16x32_bf16 v[28:31], v[228:231], v[122:125], v[28:31]
	v_exp_f32_e32 v106, v106
	v_exp_f32_e32 v107, v107
	v_exp_f32_e32 v108, v108
	v_mfma_f32_16x16x32_bf16 v[24:27], v[232:235], v[122:125], v[24:27]
	v_exp_f32_e32 v109, v109
	v_exp_f32_e32 v110, v110
	v_mfma_f32_16x16x32_bf16 v[56:59], v[232:235], v[118:121], v[56:59]
	v_exp_f32_e32 v111, v111
	v_mfma_f32_16x16x32_bf16 v[112:115], v[20:23], v[118:121], v[112:115]
	v_cvt_pk_bf16_f32 v116, v100, v101
	v_cvt_pk_bf16_f32 v117, v102, v103
	v_cvt_pk_bf16_f32 v122, v108, v109
	v_mfma_f32_16x16x32_bf16 v[64:67], v[228:231], v[118:121], v[64:67]
	v_cvt_pk_bf16_f32 v118, v104, v105
	v_cvt_pk_bf16_f32 v119, v106, v107
	v_cvt_pk_bf16_f32 v120, v92, v93
	v_cvt_pk_bf16_f32 v121, v94, v95
	v_cvt_pk_bf16_f32 v123, v110, v111
	s_nop 1
	v_mfma_f32_16x16x32_bf16 v[72:75], v[188:191], v[116:119], v[72:75]
	v_mfma_f32_16x16x32_bf16 v[36:39], v[188:191], v[120:123], v[36:39]
	v_mfma_f32_16x16x32_bf16 v[68:71], v[192:195], v[116:119], v[68:71]
	v_mfma_f32_16x16x32_bf16 v[32:35], v[192:195], v[120:123], v[32:35]
	v_mfma_f32_16x16x32_bf16 v[112:115], v[20:23], v[116:119], v[112:115]
	v_mfma_f32_16x16x32_bf16 v[76:79], v[20:23], v[120:123], v[76:79]
	v_mfma_f32_16x16x32_bf16 v[64:67], v[196:199], v[116:119], v[64:67]
	v_mfma_f32_16x16x32_bf16 v[28:31], v[196:199], v[120:123], v[28:31]
	v_mfma_f32_16x16x32_bf16 v[56:59], v[200:203], v[116:119], v[56:59]
	v_mfma_f32_16x16x32_bf16 v[24:27], v[200:203], v[120:123], v[24:27]
